# LN pipelined + tok/cache/prep loads de-serialized
# speedup vs baseline: 1.0525x; 1.0525x over previous
; __device__ __forceinline__ void ln_phase(const PP P, const float* g, const float* bta) {
;     const int tid = P.tid, lane = tid & 63, wave = tid >> 6, G = P.G;
;     float* X = P.out; bf16* XB = (bf16*)(P.ws + WS_XB);
;     for (int row = P.bid * 8 + wave; row < MT; row += G * 8) {
;         float* p = X + (size_t)row * 1024; f32x4 v[4]; float s = 0.f;
; #pragma unroll
;         for (int i = 0; i < 4; ++i) { v[i] = *(const f32x4*)(p + 256 * i + lane * 4); s += (v[i][0] + v[i][1]) + (v[i][2] + v[i][3]); }
;         const float mu = wave_sum(s) * (1.0f / 1024.0f); float q = 0.f;
; #pragma unroll
;         for (int i = 0; i < 4; ++i) { const f32x4 d = v[i] - mu; q += (d[0] * d[0] + d[1] * d[1]) + (d[2] * d[2] + d[3] * d[3]); }
;         const float rstd = __builtin_amdgcn_rsqf(wave_sum(q) * (1.0f / 1024.0f) + 1e-5f);
; __global__ void __launch_bounds__(512) mega(Params P) {
;     ...
;             case 7: ln_phase(pp, KIN(22) + l * 1024, KIN(23) + l * 1024); break;
;             case 10: ln_phase(pp, KIN(27) + l * 1024, KIN(28) + l * 1024); break;
.LBB0_8:
	v_writelane_b32 v254, s12, 11
	s_waitcnt vmcnt(1)
	v_mov_b32_e32 v3, 0x41
	v_readlane_b32 s2, v254, 9
	v_cmp_lt_i32_e64 s[4:5], s64, v3
	v_sub_u32_e64 v1, s64, 64
	v_sub_u32_e64 v0, s2, 64
	v_mov_b32_e32 v2, s2
	v_cndmask_b32_e64 v0, v0, v2, s[4:5]
	s_mov_b64 s[8:9], 0
	v_readfirstlane_b32 s2, v0
	v_mov_b32_e32 v0, s64
	v_cndmask_b32_e64 v0, v1, v0, s[4:5]
	v_writelane_b32 v254, s2, 12
	v_readfirstlane_b32 s2, v0
	s_mov_b32 s51, s91
	s_mov_b64 s[16:17], 0
	v_writelane_b32 v254, s2, 13
	s_mov_b64 s[2:3], -1
	v_readlane_b32 s6, v254, 10
	s_cmp_lt_i32 s6, 4
	v_writelane_b32 v254, s8, 14
	s_nop 1
	v_writelane_b32 v254, s9, 15
	s_cbranch_scc1 .LBB0_63
	v_readlane_b32 s8, v254, 10
	s_cmp_gt_i32 s8, 6
	s_mov_b64 s[8:9], 0
	s_mov_b64 s[6:7], 0
	v_writelane_b32 v254, s8, 14
	s_nop 1
	v_writelane_b32 v254, s9, 15
	s_cbranch_scc0 .LBB0_24
	v_readlane_b32 s2, v254, 10
	s_cmp_gt_i32 s2, 9
	s_cbranch_scc0 .LBB0_17
	s_cmp_eq_u32 s2, 10
	s_mov_b64 s[2:3], -1
	v_writelane_b32 v254, s2, 14
	s_nop 1
	v_writelane_b32 v254, s3, 15
	s_cbranch_scc0 .LBB0_16
	s_load_dwordx2 s[8:9], s[0:1], 0xd8
	s_waitcnt lgkmcnt(0)
	s_load_dwordx2 s[12:13], s[0:1], 0xe0
	s_waitcnt lgkmcnt(0)
	v_readlane_b32 s2, v254, 9
	v_readlane_b32 s3, v254, 3
	s_lshl_b32 s14, s50, 12
	s_add_u32 s8, s8, s14
	s_addc_u32 s9, s9, 0
	s_add_u32 s12, s12, s14
	s_addc_u32 s13, s13, 0
	v_and_b32_e32 v0, 63, v177
	v_lshlrev_b32_e32 v1, 4, v0
	v_lshlrev_b32_e32 v2, 3, v0
	global_load_dwordx4 v[100:103], v1, s[8:9]
	global_load_dwordx4 v[104:107], v1, s[8:9] offset:1024
	global_load_dwordx4 v[108:111], v1, s[8:9] offset:2048
	global_load_dwordx4 v[112:115], v1, s[8:9] offset:3072
	global_load_dwordx4 v[116:119], v1, s[12:13]
	global_load_dwordx4 v[120:123], v1, s[12:13] offset:1024
	global_load_dwordx4 v[124:127], v1, s[12:13] offset:2048
	global_load_dwordx4 v[128:131], v1, s[12:13] offset:3072
	s_lshl_b32 s2, s2, 3
	s_add_i32 s13, s2, s3
	s_lshl_b32 s20, s64, 3
	s_mul_hi_u32 s11, s13, 0x1000
	s_lshl_b32 s10, s13, 12
	s_add_u32 s10, s62, s10
	s_addc_u32 s11, s63, s11
	s_mul_hi_u32 s15, s13, 0x800
	s_lshl_b32 s14, s13, 11
	s_add_u32 s14, s14, 0x3060800
	s_addc_u32 s15, s15, 0
	s_add_u32 s14, s48, s14
	s_addc_u32 s15, s49, s15
	global_load_dwordx4 v[4:7], v1, s[10:11]
	global_load_dwordx4 v[8:11], v1, s[10:11] offset:1024
	global_load_dwordx4 v[12:15], v1, s[10:11] offset:2048
	global_load_dwordx4 v[16:19], v1, s[10:11] offset:3072
	s_add_u32 s12, s13, s20
	s_lshl_b32 s90, s20, 12
	s_add_u32 s18, s10, s90
	s_addc_u32 s19, s11, 0
	s_cmp_lt_u32 s12, 0x8200
	s_cselect_b32 s18, s18, s10
	s_cselect_b32 s19, s19, s11
	global_load_dwordx4 v[26:29], v1, s[18:19]
	global_load_dwordx4 v[30:33], v1, s[18:19] offset:1024
	global_load_dwordx4 v[34:37], v1, s[18:19] offset:2048
	global_load_dwordx4 v[38:41], v1, s[18:19] offset:3072
.Lln10_h0:
	s_cmp_ge_u32 s13, 0x8200
	s_cbranch_scc1 .Lln10_done
	s_waitcnt vmcnt(4)
	v_pk_add_f32 v[70:71], v[4:5], v[6:7]
	v_pk_add_f32 v[72:73], v[8:9], v[10:11]
	v_pk_add_f32 v[74:75], v[12:13], v[14:15]
	v_pk_add_f32 v[76:77], v[16:17], v[18:19]
	v_pk_add_f32 v[70:71], v[70:71], v[72:73]
	v_pk_add_f32 v[74:75], v[74:75], v[76:77]
	v_pk_add_f32 v[70:71], v[70:71], v[74:75]
	s_nop 0
	v_add_f32_e32 v70, v70, v71
	s_nop 1
	v_add_f32_dpp v70, v70, v70 quad_perm:[1,0,3,2] row_mask:0xf bank_mask:0xf bound_ctrl:1
	s_nop 1
	v_add_f32_dpp v70, v70, v70 quad_perm:[2,3,0,1] row_mask:0xf bank_mask:0xf bound_ctrl:1
	s_nop 1
	v_add_f32_dpp v70, v70, v70 row_half_mirror row_mask:0xf bank_mask:0xf bound_ctrl:1
	s_nop 1
	v_add_f32_dpp v70, v70, v70 row_mirror row_mask:0xf bank_mask:0xf bound_ctrl:1
	s_nop 1
	v_readlane_b32 s3, v70, 16
	v_readlane_b32 s9, v70, 48
	v_readlane_b32 s2, v70, 0
	v_readlane_b32 s8, v70, 32
	s_nop 1
	v_mov_b32_e32 v76, s3
	v_mov_b32_e32 v77, s9
	v_add_f32_e32 v76, s2, v76
	v_add_f32_e32 v77, s8, v77
	v_add_f32_e32 v70, v76, v77
	v_fmac_f32_e32 v4, 0xba800000, v70
	v_fmac_f32_e32 v5, 0xba800000, v70
	v_fmac_f32_e32 v6, 0xba800000, v70
	v_fmac_f32_e32 v7, 0xba800000, v70
	v_fmac_f32_e32 v8, 0xba800000, v70
	v_fmac_f32_e32 v9, 0xba800000, v70
	v_fmac_f32_e32 v10, 0xba800000, v70
	v_fmac_f32_e32 v11, 0xba800000, v70
	v_fmac_f32_e32 v12, 0xba800000, v70
	v_fmac_f32_e32 v13, 0xba800000, v70
	v_fmac_f32_e32 v14, 0xba800000, v70
	v_fmac_f32_e32 v15, 0xba800000, v70
	v_fmac_f32_e32 v16, 0xba800000, v70
	v_fmac_f32_e32 v17, 0xba800000, v70
	v_fmac_f32_e32 v18, 0xba800000, v70
	v_fmac_f32_e32 v19, 0xba800000, v70
	v_pk_mul_f32 v[72:73], v[4:5], v[4:5]
	v_pk_mul_f32 v[74:75], v[6:7], v[6:7]
	v_pk_fma_f32 v[72:73], v[8:9], v[8:9], v[72:73]
	v_pk_fma_f32 v[74:75], v[10:11], v[10:11], v[74:75]
	v_pk_fma_f32 v[72:73], v[12:13], v[12:13], v[72:73]
	v_pk_fma_f32 v[74:75], v[14:15], v[14:15], v[74:75]
	v_pk_fma_f32 v[72:73], v[16:17], v[16:17], v[72:73]
	v_pk_fma_f32 v[74:75], v[18:19], v[18:19], v[74:75]
	v_pk_add_f32 v[72:73], v[72:73], v[74:75]
	s_nop 0
	v_add_f32_e32 v71, v72, v73
	s_nop 1
	v_add_f32_dpp v71, v71, v71 quad_perm:[1,0,3,2] row_mask:0xf bank_mask:0xf bound_ctrl:1
	s_nop 1
	v_add_f32_dpp v71, v71, v71 quad_perm:[2,3,0,1] row_mask:0xf bank_mask:0xf bound_ctrl:1
	s_nop 1
	v_add_f32_dpp v71, v71, v71 row_half_mirror row_mask:0xf bank_mask:0xf bound_ctrl:1
	s_nop 1
	v_add_f32_dpp v71, v71, v71 row_mirror row_mask:0xf bank_mask:0xf bound_ctrl:1
	s_nop 1
	v_readlane_b32 s3, v71, 16
	v_readlane_b32 s9, v71, 48
	v_readlane_b32 s2, v71, 0
	v_readlane_b32 s8, v71, 32
	s_nop 1
	v_mov_b32_e32 v76, s3
	v_mov_b32_e32 v77, s9
	v_add_f32_e32 v76, s2, v76
	v_add_f32_e32 v77, s8, v77
	v_add_f32_e32 v71, v76, v77
	v_fmamk_f32 v71, v71, 0x3a800000, v164
	v_rsq_f32_e32 v72, v71
	s_nop 1
; __device__ __forceinline__ unsigned pk2(float lo, float hi) { const f32x2_ v = {lo, hi}; return __builtin_bit_cast(unsigned, __builtin_convertvector(v, bf16x2_)); }
; __device__ __forceinline__ void ln_phase(const PP P, const float* g, const float* bta) {
;     ...
;     for (int row = P.bid * 8 + wave; row < MT; row += G * 8) {
;         float* p = X + (size_t)row * 1024; f32x4 v[4]; float s = 0.f;
; #pragma unroll
;         for (int i = 0; i < 4; ++i) { v[i] = *(const f32x4*)(p + 256 * i + lane * 4); s += (v[i][0] + v[i][1]) + (v[i][2] + v[i][3]); }
;         const float mu = wave_sum(s) * (1.0f / 1024.0f); float q = 0.f;
; #pragma unroll
;         for (int i = 0; i < 4; ++i) { const f32x4 d = v[i] - mu; q += (d[0] * d[0] + d[1] * d[1]) + (d[2] * d[2] + d[3] * d[3]); }
;         const float rstd = __builtin_amdgcn_rsqf(wave_sum(q) * (1.0f / 1024.0f) + 1e-5f);
; #pragma unroll
;         for (int i = 0; i < 4; ++i) { const int col = 256 * i + lane * 4; const f32x4 gg = *(const f32x4*)(g + col), bb = *(const f32x4*)(bta + col);
;             const f32x4 y = (v[i] - mu) * rstd * gg + bb; *(f32x4*)(p + col) = y;
;             u32x2 w; w.x = pk2(y[0], y[1]); w.y = pk2(y[2], y[3]); *(u32x2*)(XB + (size_t)row * 1024 + col) = w; }
	v_pk_mul_f32 v[4:5], v[4:5], v[72:73] op_sel_hi:[1,0]
	v_pk_mul_f32 v[6:7], v[6:7], v[72:73] op_sel_hi:[1,0]
	v_pk_mul_f32 v[8:9], v[8:9], v[72:73] op_sel_hi:[1,0]
	v_pk_mul_f32 v[10:11], v[10:11], v[72:73] op_sel_hi:[1,0]
	v_pk_mul_f32 v[12:13], v[12:13], v[72:73] op_sel_hi:[1,0]
	v_pk_mul_f32 v[14:15], v[14:15], v[72:73] op_sel_hi:[1,0]
	v_pk_mul_f32 v[16:17], v[16:17], v[72:73] op_sel_hi:[1,0]
	v_pk_mul_f32 v[18:19], v[18:19], v[72:73] op_sel_hi:[1,0]
	v_pk_fma_f32 v[42:43], v[4:5], v[100:101], v[116:117]
	v_pk_fma_f32 v[44:45], v[6:7], v[102:103], v[118:119]
	v_pk_fma_f32 v[46:47], v[8:9], v[104:105], v[120:121]
	v_pk_fma_f32 v[48:49], v[10:11], v[106:107], v[122:123]
	v_pk_fma_f32 v[50:51], v[12:13], v[108:109], v[124:125]
	v_pk_fma_f32 v[52:53], v[14:15], v[110:111], v[126:127]
	v_pk_fma_f32 v[54:55], v[16:17], v[112:113], v[128:129]
	v_pk_fma_f32 v[56:57], v[18:19], v[114:115], v[130:131]
	s_lshl_b32 s12, s20, 1
	s_add_u32 s12, s13, s12
	s_lshl_b32 s90, s20, 13
	s_add_u32 s18, s10, s90
	s_addc_u32 s19, s11, 0
	s_cmp_lt_u32 s12, 0x8200
	s_cselect_b32 s18, s18, s10
	s_cselect_b32 s19, s19, s11
	global_load_dwordx4 v[4:7], v1, s[18:19]
	global_load_dwordx4 v[8:11], v1, s[18:19] offset:1024
	global_load_dwordx4 v[12:15], v1, s[18:19] offset:2048
	global_load_dwordx4 v[16:19], v1, s[18:19] offset:3072
	v_cvt_pk_bf16_f32 v58, v42, v43
	v_cvt_pk_bf16_f32 v59, v44, v45
	v_cvt_pk_bf16_f32 v60, v46, v47
	v_cvt_pk_bf16_f32 v61, v48, v49
	v_cvt_pk_bf16_f32 v62, v50, v51
	v_cvt_pk_bf16_f32 v63, v52, v53
	v_cvt_pk_bf16_f32 v64, v54, v55
	v_cvt_pk_bf16_f32 v65, v56, v57
	global_store_dwordx4 v1, v[42:45], s[10:11]
	global_store_dwordx4 v1, v[46:49], s[10:11] offset:1024
	global_store_dwordx4 v1, v[50:53], s[10:11] offset:2048
	global_store_dwordx4 v1, v[54:57], s[10:11] offset:3072
	global_store_dwordx2 v2, v[58:59], s[14:15]
	global_store_dwordx2 v2, v[60:61], s[14:15] offset:512
	global_store_dwordx2 v2, v[62:63], s[14:15] offset:1024
	global_store_dwordx2 v2, v[64:65], s[14:15] offset:1536
	s_add_u32 s13, s13, s20
	s_lshl_b32 s90, s20, 12
	s_add_u32 s10, s10, s90
	s_addc_u32 s11, s11, 0
	s_lshl_b32 s90, s20, 11
	s_add_u32 s14, s14, s90
	s_addc_u32 s15, s15, 0
.Lln10_loopB:
	s_cmp_ge_u32 s13, 0x8200
	s_cbranch_scc1 .Lln10_done
	s_waitcnt vmcnt(12)
	v_pk_add_f32 v[70:71], v[26:27], v[28:29]
	v_pk_add_f32 v[72:73], v[30:31], v[32:33]
	v_pk_add_f32 v[74:75], v[34:35], v[36:37]
	v_pk_add_f32 v[76:77], v[38:39], v[40:41]
	v_pk_add_f32 v[70:71], v[70:71], v[72:73]
	v_pk_add_f32 v[74:75], v[74:75], v[76:77]
	v_pk_add_f32 v[70:71], v[70:71], v[74:75]
	s_nop 0
	v_add_f32_e32 v70, v70, v71
	s_nop 1
	v_add_f32_dpp v70, v70, v70 quad_perm:[1,0,3,2] row_mask:0xf bank_mask:0xf bound_ctrl:1
	s_nop 1
	v_add_f32_dpp v70, v70, v70 quad_perm:[2,3,0,1] row_mask:0xf bank_mask:0xf bound_ctrl:1
	s_nop 1
	v_add_f32_dpp v70, v70, v70 row_half_mirror row_mask:0xf bank_mask:0xf bound_ctrl:1
	s_nop 1
	v_add_f32_dpp v70, v70, v70 row_mirror row_mask:0xf bank_mask:0xf bound_ctrl:1
	s_nop 1
	v_readlane_b32 s3, v70, 16
	v_readlane_b32 s9, v70, 48
	v_readlane_b32 s2, v70, 0
	v_readlane_b32 s8, v70, 32
	s_nop 1
	v_mov_b32_e32 v76, s3
	v_mov_b32_e32 v77, s9
	v_add_f32_e32 v76, s2, v76
	v_add_f32_e32 v77, s8, v77
	v_add_f32_e32 v70, v76, v77
	v_fmac_f32_e32 v26, 0xba800000, v70
	v_fmac_f32_e32 v27, 0xba800000, v70
	v_fmac_f32_e32 v28, 0xba800000, v70
	v_fmac_f32_e32 v29, 0xba800000, v70
	v_fmac_f32_e32 v30, 0xba800000, v70
	v_fmac_f32_e32 v31, 0xba800000, v70
	v_fmac_f32_e32 v32, 0xba800000, v70
	v_fmac_f32_e32 v33, 0xba800000, v70
	v_fmac_f32_e32 v34, 0xba800000, v70
	v_fmac_f32_e32 v35, 0xba800000, v70
	v_fmac_f32_e32 v36, 0xba800000, v70
	v_fmac_f32_e32 v37, 0xba800000, v70
	v_fmac_f32_e32 v38, 0xba800000, v70
	v_fmac_f32_e32 v39, 0xba800000, v70
	v_fmac_f32_e32 v40, 0xba800000, v70
	v_fmac_f32_e32 v41, 0xba800000, v70
	v_pk_mul_f32 v[72:73], v[26:27], v[26:27]
	v_pk_mul_f32 v[74:75], v[28:29], v[28:29]
	v_pk_fma_f32 v[72:73], v[30:31], v[30:31], v[72:73]
	v_pk_fma_f32 v[74:75], v[32:33], v[32:33], v[74:75]
	v_pk_fma_f32 v[72:73], v[34:35], v[34:35], v[72:73]
	v_pk_fma_f32 v[74:75], v[36:37], v[36:37], v[74:75]
	v_pk_fma_f32 v[72:73], v[38:39], v[38:39], v[72:73]
	v_pk_fma_f32 v[74:75], v[40:41], v[40:41], v[74:75]
	v_pk_add_f32 v[72:73], v[72:73], v[74:75]
	s_nop 0
	v_add_f32_e32 v71, v72, v73
	s_nop 1
	v_add_f32_dpp v71, v71, v71 quad_perm:[1,0,3,2] row_mask:0xf bank_mask:0xf bound_ctrl:1
	s_nop 1
	v_add_f32_dpp v71, v71, v71 quad_perm:[2,3,0,1] row_mask:0xf bank_mask:0xf bound_ctrl:1
	s_nop 1
	v_add_f32_dpp v71, v71, v71 row_half_mirror row_mask:0xf bank_mask:0xf bound_ctrl:1
	s_nop 1
	v_add_f32_dpp v71, v71, v71 row_mirror row_mask:0xf bank_mask:0xf bound_ctrl:1
	s_nop 1
	v_readlane_b32 s3, v71, 16
	v_readlane_b32 s9, v71, 48
	v_readlane_b32 s2, v71, 0
	v_readlane_b32 s8, v71, 32
	s_nop 1
	v_mov_b32_e32 v76, s3
	v_mov_b32_e32 v77, s9
	v_add_f32_e32 v76, s2, v76
	v_add_f32_e32 v77, s8, v77
	v_add_f32_e32 v71, v76, v77
	v_fmamk_f32 v71, v71, 0x3a800000, v164
	v_rsq_f32_e32 v72, v71
	s_nop 1
	v_pk_mul_f32 v[26:27], v[26:27], v[72:73] op_sel_hi:[1,0]
	v_pk_mul_f32 v[28:29], v[28:29], v[72:73] op_sel_hi:[1,0]
	v_pk_mul_f32 v[30:31], v[30:31], v[72:73] op_sel_hi:[1,0]
	v_pk_mul_f32 v[32:33], v[32:33], v[72:73] op_sel_hi:[1,0]
	v_pk_mul_f32 v[34:35], v[34:35], v[72:73] op_sel_hi:[1,0]
	v_pk_mul_f32 v[36:37], v[36:37], v[72:73] op_sel_hi:[1,0]
	v_pk_mul_f32 v[38:39], v[38:39], v[72:73] op_sel_hi:[1,0]
	v_pk_mul_f32 v[40:41], v[40:41], v[72:73] op_sel_hi:[1,0]
	v_pk_fma_f32 v[42:43], v[26:27], v[100:101], v[116:117]
	v_pk_fma_f32 v[44:45], v[28:29], v[102:103], v[118:119]
; __device__ __forceinline__ unsigned pk2(float lo, float hi) { const f32x2_ v = {lo, hi}; return __builtin_bit_cast(unsigned, __builtin_convertvector(v, bf16x2_)); }
; __device__ __forceinline__ void ln_phase(const PP P, const float* g, const float* bta) {
;     ...
;     for (int row = P.bid * 8 + wave; row < MT; row += G * 8) {
;         float* p = X + (size_t)row * 1024; f32x4 v[4]; float s = 0.f;
; #pragma unroll
;         for (int i = 0; i < 4; ++i) { v[i] = *(const f32x4*)(p + 256 * i + lane * 4); s += (v[i][0] + v[i][1]) + (v[i][2] + v[i][3]); }
;         const float mu = wave_sum(s) * (1.0f / 1024.0f); float q = 0.f;
; #pragma unroll
;         for (int i = 0; i < 4; ++i) { const f32x4 d = v[i] - mu; q += (d[0] * d[0] + d[1] * d[1]) + (d[2] * d[2] + d[3] * d[3]); }
;         const float rstd = __builtin_amdgcn_rsqf(wave_sum(q) * (1.0f / 1024.0f) + 1e-5f);
; #pragma unroll
;         for (int i = 0; i < 4; ++i) { const int col = 256 * i + lane * 4; const f32x4 gg = *(const f32x4*)(g + col), bb = *(const f32x4*)(bta + col);
;             const f32x4 y = (v[i] - mu) * rstd * gg + bb; *(f32x4*)(p + col) = y;
;             u32x2 w; w.x = pk2(y[0], y[1]); w.y = pk2(y[2], y[3]); *(u32x2*)(XB + (size_t)row * 1024 + col) = w; }
;     }
	v_pk_fma_f32 v[46:47], v[30:31], v[104:105], v[120:121]
	v_pk_fma_f32 v[48:49], v[32:33], v[106:107], v[122:123]
	v_pk_fma_f32 v[50:51], v[34:35], v[108:109], v[124:125]
	v_pk_fma_f32 v[52:53], v[36:37], v[110:111], v[126:127]
	v_pk_fma_f32 v[54:55], v[38:39], v[112:113], v[128:129]
	v_pk_fma_f32 v[56:57], v[40:41], v[114:115], v[130:131]
	s_lshl_b32 s12, s20, 1
	s_add_u32 s12, s13, s12
	s_lshl_b32 s90, s20, 13
	s_add_u32 s18, s10, s90
	s_addc_u32 s19, s11, 0
	s_cmp_lt_u32 s12, 0x8200
	s_cselect_b32 s18, s18, s10
	s_cselect_b32 s19, s19, s11
	global_load_dwordx4 v[26:29], v1, s[18:19]
	global_load_dwordx4 v[30:33], v1, s[18:19] offset:1024
	global_load_dwordx4 v[34:37], v1, s[18:19] offset:2048
	global_load_dwordx4 v[38:41], v1, s[18:19] offset:3072
	v_cvt_pk_bf16_f32 v58, v42, v43
	v_cvt_pk_bf16_f32 v59, v44, v45
	v_cvt_pk_bf16_f32 v60, v46, v47
	v_cvt_pk_bf16_f32 v61, v48, v49
	v_cvt_pk_bf16_f32 v62, v50, v51
	v_cvt_pk_bf16_f32 v63, v52, v53
	v_cvt_pk_bf16_f32 v64, v54, v55
	v_cvt_pk_bf16_f32 v65, v56, v57
	global_store_dwordx4 v1, v[42:45], s[10:11]
	global_store_dwordx4 v1, v[46:49], s[10:11] offset:1024
	global_store_dwordx4 v1, v[50:53], s[10:11] offset:2048
	global_store_dwordx4 v1, v[54:57], s[10:11] offset:3072
	global_store_dwordx2 v2, v[58:59], s[14:15]
	global_store_dwordx2 v2, v[60:61], s[14:15] offset:512
	global_store_dwordx2 v2, v[62:63], s[14:15] offset:1024
	global_store_dwordx2 v2, v[64:65], s[14:15] offset:1536
	s_add_u32 s13, s13, s20
	s_lshl_b32 s90, s20, 12
	s_add_u32 s10, s10, s90
	s_addc_u32 s11, s11, 0
	s_lshl_b32 s90, s20, 11
	s_add_u32 s14, s14, s90
	s_addc_u32 s15, s15, 0
.Lln10_loopA:
	s_cmp_ge_u32 s13, 0x8200
	s_cbranch_scc1 .Lln10_done
	s_waitcnt vmcnt(12)
	v_pk_add_f32 v[70:71], v[4:5], v[6:7]
	v_pk_add_f32 v[72:73], v[8:9], v[10:11]
	v_pk_add_f32 v[74:75], v[12:13], v[14:15]
	v_pk_add_f32 v[76:77], v[16:17], v[18:19]
	v_pk_add_f32 v[70:71], v[70:71], v[72:73]
	v_pk_add_f32 v[74:75], v[74:75], v[76:77]
	v_pk_add_f32 v[70:71], v[70:71], v[74:75]
	s_nop 0
	v_add_f32_e32 v70, v70, v71
	s_nop 1
	v_add_f32_dpp v70, v70, v70 quad_perm:[1,0,3,2] row_mask:0xf bank_mask:0xf bound_ctrl:1
	s_nop 1
	v_add_f32_dpp v70, v70, v70 quad_perm:[2,3,0,1] row_mask:0xf bank_mask:0xf bound_ctrl:1
	s_nop 1
	v_add_f32_dpp v70, v70, v70 row_half_mirror row_mask:0xf bank_mask:0xf bound_ctrl:1
	s_nop 1
	v_add_f32_dpp v70, v70, v70 row_mirror row_mask:0xf bank_mask:0xf bound_ctrl:1
	s_nop 1
	v_readlane_b32 s3, v70, 16
	v_readlane_b32 s9, v70, 48
	v_readlane_b32 s2, v70, 0
	v_readlane_b32 s8, v70, 32
	s_nop 1
	v_mov_b32_e32 v76, s3
	v_mov_b32_e32 v77, s9
	v_add_f32_e32 v76, s2, v76
	v_add_f32_e32 v77, s8, v77
	v_add_f32_e32 v70, v76, v77
	v_fmac_f32_e32 v4, 0xba800000, v70
	v_fmac_f32_e32 v5, 0xba800000, v70
	v_fmac_f32_e32 v6, 0xba800000, v70
	v_fmac_f32_e32 v7, 0xba800000, v70
	v_fmac_f32_e32 v8, 0xba800000, v70
	v_fmac_f32_e32 v9, 0xba800000, v70
	v_fmac_f32_e32 v10, 0xba800000, v70
	v_fmac_f32_e32 v11, 0xba800000, v70
	v_fmac_f32_e32 v12, 0xba800000, v70
	v_fmac_f32_e32 v13, 0xba800000, v70
	v_fmac_f32_e32 v14, 0xba800000, v70
	v_fmac_f32_e32 v15, 0xba800000, v70
	v_fmac_f32_e32 v16, 0xba800000, v70
	v_fmac_f32_e32 v17, 0xba800000, v70
	v_fmac_f32_e32 v18, 0xba800000, v70
	v_fmac_f32_e32 v19, 0xba800000, v70
	v_pk_mul_f32 v[72:73], v[4:5], v[4:5]
	v_pk_mul_f32 v[74:75], v[6:7], v[6:7]
	v_pk_fma_f32 v[72:73], v[8:9], v[8:9], v[72:73]
	v_pk_fma_f32 v[74:75], v[10:11], v[10:11], v[74:75]
	v_pk_fma_f32 v[72:73], v[12:13], v[12:13], v[72:73]
	v_pk_fma_f32 v[74:75], v[14:15], v[14:15], v[74:75]
	v_pk_fma_f32 v[72:73], v[16:17], v[16:17], v[72:73]
	v_pk_fma_f32 v[74:75], v[18:19], v[18:19], v[74:75]
	v_pk_add_f32 v[72:73], v[72:73], v[74:75]
	s_nop 0
	v_add_f32_e32 v71, v72, v73
	s_nop 1
	v_add_f32_dpp v71, v71, v71 quad_perm:[1,0,3,2] row_mask:0xf bank_mask:0xf bound_ctrl:1
	s_nop 1
	v_add_f32_dpp v71, v71, v71 quad_perm:[2,3,0,1] row_mask:0xf bank_mask:0xf bound_ctrl:1
	s_nop 1
	v_add_f32_dpp v71, v71, v71 row_half_mirror row_mask:0xf bank_mask:0xf bound_ctrl:1
	s_nop 1
	v_add_f32_dpp v71, v71, v71 row_mirror row_mask:0xf bank_mask:0xf bound_ctrl:1
	s_nop 1
	v_readlane_b32 s3, v71, 16
	v_readlane_b32 s9, v71, 48
	v_readlane_b32 s2, v71, 0
	v_readlane_b32 s8, v71, 32
	s_nop 1
	v_mov_b32_e32 v76, s3
	v_mov_b32_e32 v77, s9
	v_add_f32_e32 v76, s2, v76
	v_add_f32_e32 v77, s8, v77
	v_add_f32_e32 v71, v76, v77
	v_fmamk_f32 v71, v71, 0x3a800000, v164
	v_rsq_f32_e32 v72, v71
	s_nop 1
	v_pk_mul_f32 v[4:5], v[4:5], v[72:73] op_sel_hi:[1,0]
	v_pk_mul_f32 v[6:7], v[6:7], v[72:73] op_sel_hi:[1,0]
	v_pk_mul_f32 v[8:9], v[8:9], v[72:73] op_sel_hi:[1,0]
	v_pk_mul_f32 v[10:11], v[10:11], v[72:73] op_sel_hi:[1,0]
	v_pk_mul_f32 v[12:13], v[12:13], v[72:73] op_sel_hi:[1,0]
	v_pk_mul_f32 v[14:15], v[14:15], v[72:73] op_sel_hi:[1,0]
	v_pk_mul_f32 v[16:17], v[16:17], v[72:73] op_sel_hi:[1,0]
	v_pk_mul_f32 v[18:19], v[18:19], v[72:73] op_sel_hi:[1,0]
	v_pk_fma_f32 v[42:43], v[4:5], v[100:101], v[116:117]
	v_pk_fma_f32 v[44:45], v[6:7], v[102:103], v[118:119]
	v_pk_fma_f32 v[46:47], v[8:9], v[104:105], v[120:121]
	v_pk_fma_f32 v[48:49], v[10:11], v[106:107], v[122:123]
	v_pk_fma_f32 v[50:51], v[12:13], v[108:109], v[124:125]
	v_pk_fma_f32 v[52:53], v[14:15], v[110:111], v[126:127]
	v_pk_fma_f32 v[54:55], v[16:17], v[112:113], v[128:129]
	v_pk_fma_f32 v[56:57], v[18:19], v[114:115], v[130:131]
	s_lshl_b32 s12, s20, 1
	s_add_u32 s12, s13, s12
	s_lshl_b32 s90, s20, 13
	s_add_u32 s18, s10, s90
	s_addc_u32 s19, s11, 0
	s_cmp_lt_u32 s12, 0x8200
	s_cselect_b32 s18, s18, s10
	s_cselect_b32 s19, s19, s11
	global_load_dwordx4 v[4:7], v1, s[18:19]
	global_load_dwordx4 v[8:11], v1, s[18:19] offset:1024
	global_load_dwordx4 v[12:15], v1, s[18:19] offset:2048
	global_load_dwordx4 v[16:19], v1, s[18:19] offset:3072
	v_cvt_pk_bf16_f32 v58, v42, v43
	v_cvt_pk_bf16_f32 v59, v44, v45
	v_cvt_pk_bf16_f32 v60, v46, v47
	v_cvt_pk_bf16_f32 v61, v48, v49
	v_cvt_pk_bf16_f32 v62, v50, v51
	v_cvt_pk_bf16_f32 v63, v52, v53
	v_cvt_pk_bf16_f32 v64, v54, v55
	v_cvt_pk_bf16_f32 v65, v56, v57
	global_store_dwordx4 v1, v[42:45], s[10:11]
	global_store_dwordx4 v1, v[46:49], s[10:11] offset:1024
	global_store_dwordx4 v1, v[50:53], s[10:11] offset:2048
	global_store_dwordx4 v1, v[54:57], s[10:11] offset:3072
	global_store_dwordx2 v2, v[58:59], s[14:15]
	global_store_dwordx2 v2, v[60:61], s[14:15] offset:512
	global_store_dwordx2 v2, v[62:63], s[14:15] offset:1024
	global_store_dwordx2 v2, v[64:65], s[14:15] offset:1536
	s_add_u32 s13, s13, s20
	s_lshl_b32 s90, s20, 12
	s_add_u32 s10, s10, s90
	s_addc_u32 s11, s11, 0
	s_lshl_b32 s90, s20, 11
	s_add_u32 s14, s14, s90
	s_addc_u32 s15, s15, 0
	s_branch .Lln10_loopB

; __device__ __forceinline__ unsigned pk2(float lo, float hi) { const f32x2_ v = {lo, hi}; return __builtin_bit_cast(unsigned, __builtin_convertvector(v, bf16x2_)); }
; __device__ __forceinline__ void ln_phase(const PP P, const float* g, const float* bta) {
;     ...
;     float* X = P.out; bf16* XB = (bf16*)(P.ws + WS_XB);
;     for (int row = P.bid * 8 + wave; row < MT; row += G * 8) {
;         float* p = X + (size_t)row * 1024; f32x4 v[4]; float s = 0.f;
; #pragma unroll
;         for (int i = 0; i < 4; ++i) { v[i] = *(const f32x4*)(p + 256 * i + lane * 4); s += (v[i][0] + v[i][1]) + (v[i][2] + v[i][3]); }
;         const float mu = wave_sum(s) * (1.0f / 1024.0f); float q = 0.f;
; #pragma unroll
;         for (int i = 0; i < 4; ++i) { const f32x4 d = v[i] - mu; q += (d[0] * d[0] + d[1] * d[1]) + (d[2] * d[2] + d[3] * d[3]); }
;         const float rstd = __builtin_amdgcn_rsqf(wave_sum(q) * (1.0f / 1024.0f) + 1e-5f);
; #pragma unroll
;         for (int i = 0; i < 4; ++i) { const int col = 256 * i + lane * 4; const f32x4 gg = *(const f32x4*)(g + col), bb = *(const f32x4*)(bta + col);
;             const f32x4 y = (v[i] - mu) * rstd * gg + bb; *(f32x4*)(p + col) = y;
;             u32x2 w; w.x = pk2(y[0], y[1]); w.y = pk2(y[2], y[3]); *(u32x2*)(XB + (size_t)row * 1024 + col) = w; }
;     }
.LBB0_15:
	s_mov_b64 s[2:3], 0
	v_writelane_b32 v254, s2, 14
	s_nop 1
	v_writelane_b32 v254, s3, 15

; __device__ __forceinline__ void ln_phase(const PP P, const float* g, const float* bta) {
;     const int tid = P.tid, lane = tid & 63, wave = tid >> 6, G = P.G;
;     float* X = P.out; bf16* XB = (bf16*)(P.ws + WS_XB);
;     for (int row = P.bid * 8 + wave; row < MT; row += G * 8) {
;         float* p = X + (size_t)row * 1024; f32x4 v[4]; float s = 0.f;
; #pragma unroll
;         for (int i = 0; i < 4; ++i) { v[i] = *(const f32x4*)(p + 256 * i + lane * 4); s += (v[i][0] + v[i][1]) + (v[i][2] + v[i][3]); }
; __global__ void __launch_bounds__(512) mega(Params P) {
;     ...
;             case 7: ln_phase(pp, KIN(22) + l * 1024, KIN(23) + l * 1024); break;
.LBB0_17:
	s_mov_b64 s[8:9], 0
	v_writelane_b32 v254, s8, 14
	s_nop 1
	v_writelane_b32 v254, s9, 15
	s_cbranch_execz .LBB0_23
	v_readlane_b32 s2, v254, 10
	s_cmp_eq_u32 s2, 7
	s_mov_b64 s[2:3], -1
	v_writelane_b32 v254, s2, 14
	s_nop 1
	v_writelane_b32 v254, s3, 15
	s_cbranch_scc0 .LBB0_23
	s_load_dwordx2 s[8:9], s[0:1], 0xb0
	s_waitcnt lgkmcnt(0)
	s_load_dwordx2 s[12:13], s[0:1], 0xb8
	s_waitcnt lgkmcnt(0)
	v_readlane_b32 s2, v254, 9
	v_readlane_b32 s3, v254, 3
	s_lshl_b32 s14, s50, 12
	s_add_u32 s8, s8, s14
	s_addc_u32 s9, s9, 0
	s_add_u32 s12, s12, s14
	s_addc_u32 s13, s13, 0
	v_and_b32_e32 v0, 63, v177
	v_lshlrev_b32_e32 v1, 4, v0
	v_lshlrev_b32_e32 v2, 3, v0
	global_load_dwordx4 v[100:103], v1, s[8:9]
	global_load_dwordx4 v[104:107], v1, s[8:9] offset:1024
	global_load_dwordx4 v[108:111], v1, s[8:9] offset:2048
	global_load_dwordx4 v[112:115], v1, s[8:9] offset:3072
	global_load_dwordx4 v[116:119], v1, s[12:13]
	global_load_dwordx4 v[120:123], v1, s[12:13] offset:1024
	global_load_dwordx4 v[124:127], v1, s[12:13] offset:2048
	global_load_dwordx4 v[128:131], v1, s[12:13] offset:3072
	s_lshl_b32 s2, s2, 3
	s_add_i32 s13, s2, s3
	s_lshl_b32 s20, s64, 3
	s_mul_hi_u32 s11, s13, 0x1000
	s_lshl_b32 s10, s13, 12
	s_add_u32 s10, s62, s10
	s_addc_u32 s11, s63, s11
	s_mul_hi_u32 s15, s13, 0x800
	s_lshl_b32 s14, s13, 11
	s_add_u32 s14, s14, 0x3060800
	s_addc_u32 s15, s15, 0
	s_add_u32 s14, s48, s14
	s_addc_u32 s15, s49, s15
	global_load_dwordx4 v[4:7], v1, s[10:11]
	global_load_dwordx4 v[8:11], v1, s[10:11] offset:1024
	global_load_dwordx4 v[12:15], v1, s[10:11] offset:2048
	global_load_dwordx4 v[16:19], v1, s[10:11] offset:3072
	s_add_u32 s12, s13, s20
	s_lshl_b32 s90, s20, 12
	s_add_u32 s18, s10, s90
	s_addc_u32 s19, s11, 0
	s_cmp_lt_u32 s12, 0x8200
	s_cselect_b32 s18, s18, s10
	s_cselect_b32 s19, s19, s11
	global_load_dwordx4 v[26:29], v1, s[18:19]
	global_load_dwordx4 v[30:33], v1, s[18:19] offset:1024
	global_load_dwordx4 v[34:37], v1, s[18:19] offset:2048
	global_load_dwordx4 v[38:41], v1, s[18:19] offset:3072

; __device__ __forceinline__ unsigned pk2(float lo, float hi) { const f32x2_ v = {lo, hi}; return __builtin_bit_cast(unsigned, __builtin_convertvector(v, bf16x2_)); }
; __device__ __forceinline__ void cache_phase(const PP P, int l) {
;     const int tid = P.tid, G = P.G;
;     bf16* CKVB = (bf16*)(P.ws + WS_CKVB); bf16* KPEB = (bf16*)(P.ws + WS_KPEB);
;     const float* cckv = KIN(2) + (size_t)l * 32 * 2048 * 256; const float* ckpe = KIN(3) + (size_t)l * 32 * 2048 * 32;
;     for (int g = P.bid * 512 + tid; g < 65536 * 32; g += G * 512) {
;         const int prow = g >> 5, c8 = g & 31, b = prow >> 11, s = prow & 2047;
;         const float* sp = cckv + (size_t)prow * 256 + c8 * 8; const f32x4 a = *(const f32x4*)sp, c = *(const f32x4*)(sp + 4);
;         u32x4 w; w.x = pk2(a[0], a[1]); w.y = pk2(a[2], a[3]); w.z = pk2(c[0], c[1]); w.w = pk2(c[2], c[3]);
;         *(u32x4*)(CKVB + ((size_t)MP + (size_t)b * 2048 + s) * 256 + c8 * 8) = w;
;     }
.LBB0_405:
	v_readlane_b32 s4, v254, 12
	s_load_dwordx2 s[8:9], s[0:1], 16
	s_waitcnt lgkmcnt(0)
	s_load_dwordx2 s[2:3], s[0:1], 24
	s_waitcnt lgkmcnt(0)
	s_waitcnt vmcnt(0)
	v_readlane_b32 s5, v254, 13
	s_nop 3
	v_lshl_add_u32 v0, s4, 9, v177
	s_lshl_b32 s12, s5, 9
	s_lshl_b32 s13, s5, 12
	s_lshl_b32 s10, s50, 26
	s_add_u32 s8, s8, s10
	s_addc_u32 s9, s9, 0
	s_add_u32 s6, s48, 0xdac0800
	s_addc_u32 s7, s49, 0
	s_mov_b32 s14, s4
	v_cmp_gt_u32_e32 vcc, 0x200000, v0
	s_and_saveexec_b64 s[4:5], vcc
	s_cbranch_execz .Lcva_done
.Lcva_loop:
	v_mov_b32_e32 v110, v0
	v_add_u32_e32 v111, s12, v110
	v_add_u32_e32 v112, s12, v111
	v_add_u32_e32 v113, s12, v112
	v_add_u32_e32 v114, s12, v113
	v_add_u32_e32 v115, s12, v114
	v_add_u32_e32 v116, s12, v115
	v_add_u32_e32 v117, s12, v116
	v_min_u32_e32 v10, 0x1fffff, v110
	v_min_u32_e32 v11, 0x1fffff, v111
	v_min_u32_e32 v12, 0x1fffff, v112
	v_min_u32_e32 v13, 0x1fffff, v113
	v_min_u32_e32 v14, 0x1fffff, v114
	v_min_u32_e32 v15, 0x1fffff, v115
	v_min_u32_e32 v16, 0x1fffff, v116
	v_min_u32_e32 v17, 0x1fffff, v117
	v_lshlrev_b32_e32 v100, 5, v10
	v_lshlrev_b32_e32 v101, 5, v11
	v_lshlrev_b32_e32 v102, 5, v12
	v_lshlrev_b32_e32 v103, 5, v13
	v_lshlrev_b32_e32 v104, 5, v14
	v_lshlrev_b32_e32 v105, 5, v15
	v_lshlrev_b32_e32 v106, 5, v16
	v_lshlrev_b32_e32 v107, 5, v17
	global_load_dwordx4 v[30:33], v100, s[8:9]
	global_load_dwordx4 v[34:37], v100, s[8:9] offset:16
	global_load_dwordx4 v[38:41], v101, s[8:9]
	global_load_dwordx4 v[42:45], v101, s[8:9] offset:16
	global_load_dwordx4 v[46:49], v102, s[8:9]
	global_load_dwordx4 v[50:53], v102, s[8:9] offset:16
	global_load_dwordx4 v[54:57], v103, s[8:9]
	global_load_dwordx4 v[58:61], v103, s[8:9] offset:16
	global_load_dwordx4 v[62:65], v104, s[8:9]
	global_load_dwordx4 v[66:69], v104, s[8:9] offset:16
	global_load_dwordx4 v[70:73], v105, s[8:9]
	global_load_dwordx4 v[74:77], v105, s[8:9] offset:16
	global_load_dwordx4 v[78:81], v106, s[8:9]
	global_load_dwordx4 v[82:85], v106, s[8:9] offset:16
	global_load_dwordx4 v[86:89], v107, s[8:9]
	global_load_dwordx4 v[90:93], v107, s[8:9] offset:16
	v_lshlrev_b32_e32 v10, 4, v10
	v_lshlrev_b32_e32 v11, 4, v11
	v_lshlrev_b32_e32 v12, 4, v12
	v_lshlrev_b32_e32 v13, 4, v13
	v_lshlrev_b32_e32 v14, 4, v14
	v_lshlrev_b32_e32 v15, 4, v15
	v_lshlrev_b32_e32 v16, 4, v16
	v_lshlrev_b32_e32 v17, 4, v17
	v_add_u32_e32 v0, s13, v0
	s_waitcnt vmcnt(14)
	v_cvt_pk_bf16_f32 v30, v30, v31
	v_cvt_pk_bf16_f32 v31, v32, v33
	v_cvt_pk_bf16_f32 v32, v34, v35
	v_cvt_pk_bf16_f32 v33, v36, v37
	s_waitcnt vmcnt(12)
	v_cvt_pk_bf16_f32 v38, v38, v39
	v_cvt_pk_bf16_f32 v39, v40, v41
	v_cvt_pk_bf16_f32 v40, v42, v43
	v_cvt_pk_bf16_f32 v41, v44, v45
	s_waitcnt vmcnt(10)
	v_cvt_pk_bf16_f32 v46, v46, v47
	v_cvt_pk_bf16_f32 v47, v48, v49
	v_cvt_pk_bf16_f32 v48, v50, v51
	v_cvt_pk_bf16_f32 v49, v52, v53
	s_waitcnt vmcnt(8)
	v_cvt_pk_bf16_f32 v54, v54, v55
	v_cvt_pk_bf16_f32 v55, v56, v57
	v_cvt_pk_bf16_f32 v56, v58, v59
	v_cvt_pk_bf16_f32 v57, v60, v61
	s_waitcnt vmcnt(6)
	v_cvt_pk_bf16_f32 v62, v62, v63
	v_cvt_pk_bf16_f32 v63, v64, v65
	v_cvt_pk_bf16_f32 v64, v66, v67
	v_cvt_pk_bf16_f32 v65, v68, v69
	s_waitcnt vmcnt(4)
	v_cvt_pk_bf16_f32 v70, v70, v71
	v_cvt_pk_bf16_f32 v71, v72, v73
	v_cvt_pk_bf16_f32 v72, v74, v75
	v_cvt_pk_bf16_f32 v73, v76, v77
	s_waitcnt vmcnt(2)
	v_cvt_pk_bf16_f32 v78, v78, v79
	v_cvt_pk_bf16_f32 v79, v80, v81
	v_cvt_pk_bf16_f32 v80, v82, v83
	v_cvt_pk_bf16_f32 v81, v84, v85
	s_waitcnt vmcnt(0)
	v_cvt_pk_bf16_f32 v86, v86, v87
	v_cvt_pk_bf16_f32 v87, v88, v89
	v_cvt_pk_bf16_f32 v88, v90, v91
	v_cvt_pk_bf16_f32 v89, v92, v93
	global_store_dwordx4 v10, v[30:33], s[6:7]
	v_cmp_gt_u32_e32 vcc, 0x200000, v111
	s_and_saveexec_b64 s[10:11], vcc
	global_store_dwordx4 v11, v[38:41], s[6:7]
	s_mov_b64 exec, s[10:11]
	v_cmp_gt_u32_e32 vcc, 0x200000, v112
	s_and_saveexec_b64 s[10:11], vcc
	global_store_dwordx4 v12, v[46:49], s[6:7]
	s_mov_b64 exec, s[10:11]
	v_cmp_gt_u32_e32 vcc, 0x200000, v113
	s_and_saveexec_b64 s[10:11], vcc
	global_store_dwordx4 v13, v[54:57], s[6:7]
	s_mov_b64 exec, s[10:11]
	v_cmp_gt_u32_e32 vcc, 0x200000, v114
	s_and_saveexec_b64 s[10:11], vcc
	global_store_dwordx4 v14, v[62:65], s[6:7]
	s_mov_b64 exec, s[10:11]
	v_cmp_gt_u32_e32 vcc, 0x200000, v115
	s_and_saveexec_b64 s[10:11], vcc
	global_store_dwordx4 v15, v[70:73], s[6:7]
	s_mov_b64 exec, s[10:11]
	v_cmp_gt_u32_e32 vcc, 0x200000, v116
	s_and_saveexec_b64 s[10:11], vcc
	global_store_dwordx4 v16, v[78:81], s[6:7]
	s_mov_b64 exec, s[10:11]
	v_cmp_gt_u32_e32 vcc, 0x200000, v117
	s_and_saveexec_b64 s[10:11], vcc
	global_store_dwordx4 v17, v[86:89], s[6:7]
	s_mov_b64 exec, s[10:11]
	v_cmp_gt_u32_e32 vcc, 0x200000, v0
	s_and_b64 exec, exec, vcc
	s_cbranch_execnz .Lcva_loop
; __device__ __forceinline__ unsigned pk2(float lo, float hi) { const f32x2_ v = {lo, hi}; return __builtin_bit_cast(unsigned, __builtin_convertvector(v, bf16x2_)); }
; __device__ __forceinline__ void prep_phase(const PP P, LAS unsigned char* lds, const int wl, const bool do_rest) {
;     ...
;     for (int it = P.bid; it < 3080; it += G) {
;         const int l = wl, r = it;
;         const float* src; int ld, K, kt_n, tt; bf16* dst; int kind;
;         if (r < 576)       { kind = 0; tt = r;        src = KIN(7) + (size_t)l * 1024 * 2216;  ld = 2216; K = 1024; kt_n = 16; dst = WB + l * W_LAYER + W_IN; }
;         else if (r < 648)  { kind = 1; tt = r - 576;  src = KIN(9) + (size_t)l * 384 * 768;    ld = 768;  K = 384;  kt_n = 6;  dst = WB + l * W_LAYER + W_UQ; }
;         else if (r < 680)  { kind = 1; tt = r - 648;  src = KIN(11) + (size_t)l * 256 * 512;   ld = 512;  K = 256;  kt_n = 4;  dst = WB + l * W_LAYER + W_UK; }
;         else if (r < 712)  { kind = 1; tt = r - 680;  src = KIN(12) + (size_t)l * 256 * 512;   ld = 512;  K = 256;  kt_n = 4;  dst = WB + l * W_LAYER + W_UVT; }
;         else if (r < 968)  { kind = 1; tt = r - 712;  src = KIN(21) + (size_t)l * 1024 * 1024; ld = 1024; K = 1024; kt_n = 16; dst = WB + l * W_LAYER + W_OUT; }
;         else if (r < 2376) { kind = 2; tt = r - 968;  src = nullptr;                            ld = 2816; K = 1024; kt_n = 16; dst = WB + l * W_LAYER + W_GU; }
;         else               { kind = 1; tt = r - 2376; src = KIN(26) + (size_t)l * 2816 * 1024; ld = 1024; K = 2816; kt_n = 44; dst = WB + l * W_LAYER + W_DN; }
;         const int n0 = (tt / kt_n) * 64, k0 = (tt % kt_n) * 64;
; __device__ __forceinline__ void cache_phase(const PP P, int l) {
;     ...
;     for (int g = P.bid * 512 + tid; g < 65536 * 4; g += G * 512) {
;         const int prow = g >> 2, c8 = g & 3, b = prow >> 11, s = prow & 2047;
;         const float* sp = ckpe + (size_t)prow * 32 + c8 * 8; const f32x4 a = *(const f32x4*)sp, c = *(const f32x4*)(sp + 4);
;         u32x4 w; w.x = pk2(a[0], a[1]); w.y = pk2(a[2], a[3]); w.z = pk2(c[0], c[1]); w.w = pk2(c[2], c[3]);
;         *(u32x4*)(KPEB + ((size_t)MP + (size_t)b * 2048 + s) * 32 + c8 * 8) = w;
;     }
.Lcva_done:
	s_mov_b64 exec, s[4:5]
	v_lshl_add_u32 v0, s14, 9, v177
	s_lshl_b32 s10, s50, 23
	s_add_u32 s2, s2, s10
	s_addc_u32 s3, s3, 0
	s_add_u32 s6, s48, 0xfd00800
	s_addc_u32 s7, s49, 0
	s_mul_i32 s13, s12, 3
	v_cmp_gt_u32_e32 vcc, 0x40000, v0
	s_and_saveexec_b64 s[4:5], vcc
	s_cbranch_execz .Lcvb_done
.Lcvb_loop:
	v_mov_b32_e32 v110, v0
	v_add_u32_e32 v111, s12, v110
	v_add_u32_e32 v112, s12, v111
	v_min_u32_e32 v10, 0x3ffff, v110
	v_min_u32_e32 v11, 0x3ffff, v111
	v_min_u32_e32 v12, 0x3ffff, v112
	v_lshlrev_b32_e32 v100, 5, v10
	v_lshlrev_b32_e32 v101, 5, v11
	v_lshlrev_b32_e32 v102, 5, v12
	global_load_dwordx4 v[30:33], v100, s[2:3]
	global_load_dwordx4 v[34:37], v100, s[2:3] offset:16
	global_load_dwordx4 v[38:41], v101, s[2:3]
	global_load_dwordx4 v[42:45], v101, s[2:3] offset:16
	global_load_dwordx4 v[46:49], v102, s[2:3]
	global_load_dwordx4 v[50:53], v102, s[2:3] offset:16
	v_lshlrev_b32_e32 v10, 4, v10
	v_lshlrev_b32_e32 v11, 4, v11
	v_lshlrev_b32_e32 v12, 4, v12
	v_add_u32_e32 v0, s13, v0
	s_waitcnt vmcnt(4)
	v_cvt_pk_bf16_f32 v30, v30, v31
	v_cvt_pk_bf16_f32 v31, v32, v33
	v_cvt_pk_bf16_f32 v32, v34, v35
	v_cvt_pk_bf16_f32 v33, v36, v37
	s_waitcnt vmcnt(2)
	v_cvt_pk_bf16_f32 v38, v38, v39
	v_cvt_pk_bf16_f32 v39, v40, v41
	v_cvt_pk_bf16_f32 v40, v42, v43
	v_cvt_pk_bf16_f32 v41, v44, v45
	s_waitcnt vmcnt(0)
	v_cvt_pk_bf16_f32 v46, v46, v47
	v_cvt_pk_bf16_f32 v47, v48, v49
	v_cvt_pk_bf16_f32 v48, v50, v51
	v_cvt_pk_bf16_f32 v49, v52, v53
	global_store_dwordx4 v10, v[30:33], s[6:7]
	v_cmp_gt_u32_e32 vcc, 0x40000, v111
	s_and_saveexec_b64 s[10:11], vcc
	global_store_dwordx4 v11, v[38:41], s[6:7]
	s_mov_b64 exec, s[10:11]
	v_cmp_gt_u32_e32 vcc, 0x40000, v112
	s_and_saveexec_b64 s[10:11], vcc
	global_store_dwordx4 v12, v[46:49], s[6:7]
	s_mov_b64 exec, s[10:11]
	v_cmp_gt_u32_e32 vcc, 0x40000, v0
	s_and_b64 exec, exec, vcc
	s_cbranch_execnz .Lcvb_loop
.Lcvb_done:
	s_mov_b64 exec, s[4:5]
	s_waitcnt vmcnt(0)
.LBB0_411:
	s_cmp_lg_u32 s50, 0
	s_cbranch_scc1 .LBB0_464
	v_readlane_b32 s2, v254, 12
	s_cmpk_gt_i32 s2, 0xc07
	s_cbranch_scc1 .LBB0_464
	s_add_u32 s2, s48, 0x1810000
	s_addc_u32 s3, s49, 0
	s_add_u32 s14, s48, 0x2aa0000
	s_addc_u32 s15, s49, 0
	s_add_u32 s16, s48, 0x1fa0000
	s_addc_u32 s17, s49, 0
	v_max_i32_e32 v3, 56, v26
	s_add_u32 s18, s48, 0x1da0000
	v_sub_u32_e32 v3, v3, v26
	s_addc_u32 s19, s49, 0
	v_add_u32_e32 v3, 7, v3
	s_add_u32 s20, s48, 0x1d60000
	v_lshrrev_b32_e32 v4, 3, v3
	s_addc_u32 s21, s49, 0
	v_add_u32_e32 v5, 1, v4
	v_add_u32_e32 v4, -1, v4
	v_and_b32_e32 v0, 63, v177
	s_add_u32 s22, s48, 0x1d20000
	v_lshrrev_b32_e32 v6, 1, v4
	v_cmp_lt_u32_e64 s[6:7], 7, v3
	v_and_b32_e32 v3, 0x3ffffffe, v5
	s_movk_i32 s26, 0x104
	s_addc_u32 s23, s49, 0
	v_lshlrev_b32_e32 v2, 2, v0
	v_lshlrev_b32_e32 v1, 8, v0
	v_add_u32_e32 v7, 1, v6
	v_lshl_add_u32 v6, v3, 3, v26
	v_cmp_ne_u32_e64 s[12:13], v5, v3
	v_mul_lo_u32 v3, v26, s26
	s_add_u32 s24, s48, 0x1c90000
	v_add3_u32 v1, 0, v2, v1
	v_cmp_lt_u32_e64 s[8:9], 1, v4
	v_and_b32_e32 v4, 2, v4
	v_add3_u32 v8, v3, v2, 0
	v_mul_u32_u24_e32 v2, 0x104, v0
	v_lshlrev_b32_e32 v9, 2, v26
	s_addc_u32 s25, s49, 0
	v_cmp_gt_i32_e64 s[4:5], 64, v26
	v_add_u32_e32 v27, 8, v26
	v_and_b32_e32 v7, -2, v7
	v_cmp_eq_u32_e64 s[10:11], 0, v4
	v_add3_u32 v10, v2, v9, 0
	s_movk_i32 s92, 0x104
	v_mad_u32_u24 v11, v0, s26, 0
	v_readlane_b32 s46, v254, 12
	s_branch .LBB0_415

; __device__ __forceinline__ void prep_phase(const PP P, LAS unsigned char* lds, const int wl, const bool do_rest) {
;     ...
; #pragma unroll
;         for (int kk = ty; kk < 64; kk += 8) tile[kk * 65 + tx] = valid ? src[(size_t)(k0 + kk) * ld + col0 + tx] : 0.f;
.LBB0_444:
	s_mul_i32 s42, s42, s51
	s_sub_i32 s40, s45, s42
	s_lshl_b32 s40, s40, 6
	s_and_saveexec_b64 s[42:43], s[4:5]
	s_cbranch_execz .LBB0_449
	v_or_b32_e32 v2, s47, v0
	s_movk_i32 s41, 0x8a8
	v_cmp_gt_i32_e32 vcc, s41, v2
	s_ashr_i32 s45, s44, 31
	s_or_b64 s[30:31], s[30:31], vcc
	s_lshl_b64 s[44:45], s[44:45], 2
	s_add_u32 s34, s34, s44
	s_addc_u32 s35, s35, s45
	v_lshlrev_b32_e32 v24, 2, v0
	v_lshl_add_u64 v[2:3], s[34:35], 0, v[24:25]
	s_mov_b64 s[34:35], 0
	v_mov_b32_e32 v4, v8
	v_mov_b32_e32 v5, v26
	v_add_u32_e32 v40, s40, v26
	v_mul_lo_u32 v40, v40, s36
	v_mov_b32_e32 v41, v25
	v_lshl_add_u64 v[40:41], v[40:41], 2, v[2:3]
	s_lshl_b32 s44, s36, 5
	s_mov_b32 s45, 0
	v_lshl_add_u64 v[42:43], v[40:41], 0, s[44:45]
	v_lshl_add_u64 v[44:45], v[42:43], 0, s[44:45]
	v_lshl_add_u64 v[46:47], v[44:45], 0, s[44:45]
	v_lshl_add_u64 v[48:49], v[46:47], 0, s[44:45]
	v_lshl_add_u64 v[50:51], v[48:49], 0, s[44:45]
	v_lshl_add_u64 v[52:53], v[50:51], 0, s[44:45]
	v_lshl_add_u64 v[54:55], v[52:53], 0, s[44:45]
	v_mov_b32_e32 v30, 0
	v_mov_b32_e32 v31, 0
	v_mov_b32_e32 v32, 0
	v_mov_b32_e32 v33, 0
	v_mov_b32_e32 v34, 0
	v_mov_b32_e32 v35, 0
	v_mov_b32_e32 v36, 0
	v_mov_b32_e32 v37, 0
	s_and_saveexec_b64 s[52:53], s[30:31]
	s_cbranch_execz .Lprepa_nold
	global_load_dword v30, v[40:41], off
	global_load_dword v31, v[42:43], off
	global_load_dword v32, v[44:45], off
	global_load_dword v33, v[46:47], off
	global_load_dword v34, v[48:49], off
	global_load_dword v35, v[50:51], off
	global_load_dword v36, v[52:53], off
	global_load_dword v37, v[54:55], off
.Lprepa_nold:
	s_or_b64 exec, exec, s[52:53]
	s_waitcnt vmcnt(7)
	ds_write_b32 v8, v30
	s_waitcnt vmcnt(6)
	ds_write_b32 v8, v31 offset:2080
	s_waitcnt vmcnt(5)
	ds_write_b32 v8, v32 offset:4160
	s_waitcnt vmcnt(4)
	ds_write_b32 v8, v33 offset:6240
	s_waitcnt vmcnt(3)
	ds_write_b32 v8, v34 offset:8320
	s_waitcnt vmcnt(2)
	ds_write_b32 v8, v35 offset:10400
	s_waitcnt vmcnt(1)
	ds_write_b32 v8, v36 offset:12480
	s_waitcnt vmcnt(0)
	ds_write_b32 v8, v37 offset:14560

; __device__ __forceinline__ void tok_phase(const PP P, int l) {
;     ...
;     for (int row = P.bid * 8 + wave; row < MT; row += G * 8) {
;         const bf16* hr = H + (size_t)row * HLD;
;         const bool smp = row >= MP; int b, t, pos;
;         if (!smp) { b = row >> 11; t = row & 2047; pos = t; } else { const int rr = row - MP; b = rr >> 4; t = rr & 15; pos = 2048 + t; }
;         const size_t krow = smp ? (size_t)MP + 65536 + (size_t)b * 16 + t : (size_t)row;
;         { float v[6]; float ss = 0.f;
; #pragma unroll
;           for (int i = 0; i < 3; ++i) { const unsigned w = *(const unsigned*)(hr + 128 * i + lane * 2); v[2 * i] = bf2f(w & 0xffffu); v[2 * i + 1] = bf2f(w >> 16); ss += v[2 * i] * v[2 * i] + v[2 * i + 1] * v[2 * i + 1]; }
;           ss = wave_sum(ss); const float rinv = __builtin_amdgcn_rsqf(ss * (1.0f / 384.0f) + 1e-6f);
; #pragma unroll
;           for (int i = 0; i < 3; ++i) { const int col = 128 * i + lane * 2; *(unsigned*)(CQN + (size_t)row * 384 + col) = pk2(v[2 * i] * rinv * qn[col], v[2 * i + 1] * rinv * qn[col + 1]); } }
;         { const u32x2 w = *(const u32x2*)(hr + C_CKV + lane * 4);
;           float v0 = bf2f(w.x & 0xffffu), v1 = bf2f(w.x >> 16), v2 = bf2f(w.y & 0xffffu), v3 = bf2f(w.y >> 16);
;           float ss = wave_sum(v0 * v0 + v1 * v1 + v2 * v2 + v3 * v3); const float rinv = __builtin_amdgcn_rsqf(ss * (1.0f / 256.0f) + 1e-6f);
;           const f32x4 gn = *(const f32x4*)(kvn + lane * 4);
;           f32x4 o; o[0] = v0 * rinv * gn[0]; o[1] = v1 * rinv * gn[1]; o[2] = v2 * rinv * gn[2]; o[3] = v3 * rinv * gn[3];
;           float* op = smp ? out + O_CKVS + ((size_t)(l * 32 + b) * 16 + t) * 256 : out + O_CKVP + ((size_t)(l * 16 + b) * 2048 + t) * 256;
;           *(f32x4*)(op + lane * 4) = o;
;           u32x2 pw; pw.x = pk2(o[0], o[1]); pw.y = pk2(o[2], o[3]); *(u32x2*)(CKVB + krow * 256 + lane * 4) = pw; }
;         if (lane < 16) { const float x1 = bf2f(hr[C_KPE + lane]), x2 = bf2f(hr[C_KPE + 16 + lane]); const float2 cs = rope[pos * 16 + lane];
;           const float o1 = x1 * cs.x - x2 * cs.y, o2 = x1 * cs.y + x2 * cs.x;
;           float* op = smp ? out + O_KPES + ((size_t)(l * 32 + b) * 16 + t) * 32 : out + O_KPEP + ((size_t)(l * 16 + b) * 2048 + t) * 32;
;           op[lane] = o1; op[16 + lane] = o2; KPEB[krow * 32 + lane] = (bf16)f2bf(o1); KPEB[krow * 32 + 16 + lane] = (bf16)f2bf(o2); }
.LBB0_469:
	v_ashrrev_i32_e32 v29, 31, v1
	v_cmp_lt_i32_e64 s[4:5], s93, v1
	v_cmp_gt_i32_e64 s[6:7], s33, v1
	s_and_saveexec_b64 s[8:9], s[6:7]
	s_xor_b64 s[8:9], exec, s[8:9]
	v_ashrrev_i32_e32 v16, 11, v1
	v_and_b32_e32 v28, 0x7ff, v1
	s_or_saveexec_b64 s[8:9], s[8:9]
	v_mov_b64_e32 v[20:21], 21
	v_mov_b64_e32 v[22:23], 0x8200000
	v_mov_b32_e32 v21, s16
	v_mov_b32_e32 v31, v28
	s_xor_b64 exec, exec, s[8:9]
	v_add_u32_e32 v15, 0xffff8000, v1
	v_and_b32_e32 v31, 15, v1
	v_mov_b64_e32 v[20:21], 14
	v_lshrrev_b32_e32 v16, 4, v15
	v_or_b32_e32 v28, 0x800, v31
	v_mov_b64_e32 v[22:23], 0xcd38000
	v_mov_b32_e32 v21, s17
	s_or_b64 exec, exec, s[8:9]
	v_mov_b64_e32 v[18:19], s[20:21]
	v_mad_i64_i32 v[18:19], s[8:9], v1, s99, v[18:19]
	v_mov_b32_e32 v15, v25
	v_lshl_add_u64 v[32:33], v[18:19], 0, v[14:15]
	global_load_dword v15, v[32:33], off
	global_load_dword v42, v[32:33], off offset:256
	global_load_dword v45, v[32:33], off offset:512
	s_nop 0
	global_load_dwordx2 v[32:33], v[8:9], off
	global_load_dwordx2 v[34:35], v[8:9], off offset:512
	global_load_dwordx2 v[36:37], v[8:9], off offset:1024
	v_lshl_add_u64 v[62:63], v[26:27], 1, v[18:19]
	v_mov_b32_e32 v66, v0
	v_mov_b32_e32 v67, v25
	v_lshl_or_b32 v68, v28, 4, v0
	v_mov_b32_e32 v69, v25
	global_load_dwordx2 v[52:53], v[62:63], off offset:768
	global_load_dwordx4 v[54:57], v[2:3], off
	v_lshl_add_u64 v[64:65], v[66:67], 1, v[18:19]
	v_lshl_add_u64 v[68:69], v[68:69], 3, s[10:11]
	global_load_ushort v58, v[64:65], off offset:1280
	global_load_ushort v59, v[64:65], off offset:1312
	global_load_dwordx2 v[60:61], v[68:69], off
	s_movk_i32 s8, 0x300
	v_mad_i64_i32 v[38:39], s[8:9], v1, s8, v[10:11]
	v_ashrrev_i32_e32 v17, 31, v16
	v_or_b32_e32 v24, 0x18000, v31
	s_waitcnt vmcnt(10)
	v_lshlrev_b32_e32 v40, 16, v15
	v_and_b32_e32 v41, 0xffff0000, v15
	s_waitcnt vmcnt(8)
	v_lshlrev_b32_e32 v44, 16, v45
	v_lshlrev_b32_e32 v43, 16, v42
	v_and_b32_e32 v42, 0xffff0000, v42
	v_and_b32_e32 v45, 0xffff0000, v45
	v_mov_b32_e32 v48, v40
	v_mov_b32_e32 v49, v44
	v_pk_mul_f32 v[46:47], v[42:43], v[42:43]
	v_mov_b32_e32 v50, v41
	v_mov_b32_e32 v51, v45
	v_pk_mul_f32 v[48:49], v[48:49], v[48:49]
	v_add_f32_e32 v15, v46, v47
	v_pk_fma_f32 v[46:47], v[50:51], v[50:51], v[48:49]
	v_lshl_add_u64 v[48:49], v[16:17], 4, v[24:25]
	v_add_f32_e32 v15, v46, v15
	v_add_f32_e32 v15, v15, v47
	v_lshlrev_b32_e32 v24, 1, v26
	v_lshl_add_u64 v[50:51], v[18:19], 0, v[24:25]
	v_add_f32_dpp v15, v15, v15 quad_perm:[1,0,3,2] row_mask:0xf bank_mask:0xf bound_ctrl:1
	s_nop 1
	v_add_f32_dpp v15, v15, v15 quad_perm:[2,3,0,1] row_mask:0xf bank_mask:0xf bound_ctrl:1
	s_nop 1
	v_add_f32_dpp v15, v15, v15 row_half_mirror row_mask:0xf bank_mask:0xf bound_ctrl:1
	s_nop 1
	v_add_f32_dpp v15, v15, v15 row_mirror row_mask:0xf bank_mask:0xf bound_ctrl:1
	s_nop 0
	v_readlane_b32 s14, v15, 16
	v_readlane_b32 s15, v15, 48
	v_readlane_b32 s8, v15, 0
	v_readlane_b32 s9, v15, 32
	v_mov_b32_e32 v46, s14
	v_mov_b32_e32 v47, s15
	v_pk_add_f32 v[46:47], s[8:9], v[46:47]
	s_nop 0
	v_add_f32_e32 v15, v46, v47
	v_fmamk_f32 v15, v15, 0x3b2aaaab, v165
	v_rsq_f32_e32 v46, v15
	s_nop 0
	v_pk_mul_f32 v[40:41], v[46:47], v[40:41] op_sel_hi:[0,1]
	v_pk_mul_f32 v[42:43], v[46:47], v[42:43] op_sel_hi:[0,1]
	v_pk_mul_f32 v[44:45], v[46:47], v[44:45] op_sel_hi:[0,1]
	s_waitcnt vmcnt(7)
	v_pk_mul_f32 v[32:33], v[32:33], v[40:41]
	s_waitcnt vmcnt(6)
	v_pk_mul_f32 v[34:35], v[34:35], v[42:43] op_sel:[0,1] op_sel_hi:[1,0]
	s_waitcnt vmcnt(5)
	v_pk_mul_f32 v[36:37], v[44:45], v[36:37]
	v_cvt_pk_bf16_f32 v15, v32, v33
	v_cvt_pk_bf16_f32 v17, v34, v35
	v_cvt_pk_bf16_f32 v24, v36, v37
	global_store_dword v[38:39], v15, off
	global_store_dword v[38:39], v17, off offset:256
	global_store_dword v[38:39], v24, off offset:512
	v_add_u32_e32 v40, v16, v21
	v_ashrrev_i32_e32 v41, 31, v40
	v_lshlrev_b64 v[20:21], v20, v[40:41]
	v_lshl_add_u64 v[38:39], s[62:63], 0, v[22:23]
	v_lshlrev_b32_e32 v24, 8, v31
	v_lshl_add_u64 v[20:21], v[38:39], 0, v[20:21]
	v_cndmask_b32_e64 v23, v29, v49, s[4:5]
	v_cndmask_b32_e64 v22, v1, v48, s[4:5]
	v_lshl_add_u64 v[20:21], v[24:25], 2, v[20:21]
	v_lshlrev_b32_e32 v24, 2, v26
	v_lshlrev_b64 v[38:39], 9, v[22:23]
	v_lshl_add_u64 v[20:21], v[20:21], 0, v[24:25]
	v_lshl_add_u64 v[38:39], v[4:5], 0, v[38:39]
	v_lshlrev_b32_e32 v24, 1, v0
	s_waitcnt vmcnt(7)
	v_lshlrev_b32_e32 v40, 16, v52
	v_and_b32_e32 v41, 0xffff0000, v52
	v_lshlrev_b32_e32 v36, 16, v53
	v_and_b32_e32 v37, 0xffff0000, v53
	v_pk_mul_f32 v[42:43], v[40:41], v[40:41]
	v_pk_mul_f32 v[44:45], v[36:37], v[36:37]
	v_add_f32_e32 v15, v42, v43
	v_add_f32_e32 v15, v44, v15
	v_add_f32_e32 v15, v45, v15
	s_nop 1
	v_add_f32_dpp v15, v15, v15 quad_perm:[1,0,3,2] row_mask:0xf bank_mask:0xf bound_ctrl:1
	s_nop 1
	v_add_f32_dpp v15, v15, v15 quad_perm:[2,3,0,1] row_mask:0xf bank_mask:0xf bound_ctrl:1
	s_nop 1
	v_add_f32_dpp v15, v15, v15 row_half_mirror row_mask:0xf bank_mask:0xf bound_ctrl:1
	s_nop 1
	v_add_f32_dpp v15, v15, v15 row_mirror row_mask:0xf bank_mask:0xf bound_ctrl:1
	s_nop 0
	v_readlane_b32 s14, v15, 16
	v_readlane_b32 s15, v15, 48
	v_readlane_b32 s8, v15, 0
	v_readlane_b32 s9, v15, 32
	v_mov_b32_e32 v42, s14
	v_mov_b32_e32 v43, s15
	v_pk_add_f32 v[42:43], s[8:9], v[42:43]
	s_nop 0
	v_add_f32_e32 v15, v42, v43
	v_fmamk_f32 v15, v15, 0x3b800000, v165
	v_rsq_f32_e32 v42, v15
	s_nop 0
	v_pk_mul_f32 v[40:41], v[42:43], v[40:41] op_sel_hi:[0,1]
	v_pk_mul_f32 v[36:37], v[42:43], v[36:37] op_sel_hi:[0,1]
	s_waitcnt vmcnt(6)
	v_pk_mul_f32 v[32:33], v[54:55], v[40:41]
	v_pk_mul_f32 v[34:35], v[56:57], v[36:37]
	global_store_dwordx4 v[20:21], v[32:35], off
	v_cvt_pk_bf16_f32 v20, v32, v33
	v_cvt_pk_bf16_f32 v21, v34, v35
	global_store_dwordx2 v[38:39], v[20:21], off
	v_lshlrev_b32_e32 v20, 2, v0
	s_and_saveexec_b64 s[8:9], vcc
	s_cbranch_execz .LBB0_475
	v_mov_b32_e32 v36, s16
	v_mov_b32_e32 v37, s17
	v_cndmask_b32_e64 v36, v36, v37, s[4:5]
	v_add_u32_e32 v36, v16, v36
	v_cndmask_b32_e64 v34, v169, v170, s[4:5]
	v_mov_b32_e32 v35, v25
	v_cndmask_b32_e64 v38, 18, 11, s[4:5]
	v_ashrrev_i32_e32 v37, 31, v36
	v_lshl_add_u64 v[34:35], s[62:63], 0, v[34:35]
	v_lshlrev_b64 v[36:37], v38, v[36:37]
	v_lshlrev_b32_e32 v32, 5, v31
	v_mov_b32_e32 v33, v25
	v_lshl_add_u64 v[34:35], v[34:35], 0, v[36:37]
	v_mov_b32_e32 v21, v25
	v_lshl_add_u64 v[32:33], v[32:33], 2, v[34:35]
	v_lshl_add_u64 v[32:33], v[32:33], 0, v[20:21]
	v_lshlrev_b64 v[22:23], 6, v[22:23]
	v_lshl_add_u64 v[22:23], v[6:7], 0, v[22:23]
	s_waitcnt vmcnt(7)
	v_lshlrev_b32_e32 v15, 16, v58
	s_waitcnt vmcnt(6)
	v_lshlrev_b32_e32 v17, 16, v59
	s_waitcnt vmcnt(5)
	v_mul_f32_e32 v21, v61, v17
	v_mul_f32_e32 v17, v60, v17
	v_fma_f32 v21, v60, v15, -v21
	v_fmac_f32_e32 v17, v61, v15
	v_cvt_pk_bf16_f32 v15, v21, s0
	global_store_dword v[32:33], v21, off
	global_store_dword v[32:33], v17, off offset:64
	v_cvt_pk_bf16_f32 v17, v17, s0
	global_store_short v[22:23], v15, off
	global_store_short v[22:23], v17, off offset:32

; __device__ __forceinline__ float sigmoidf_(float x) { return __builtin_amdgcn_rcpf(1.0f + __expf(-x)); }
; __device__ __forceinline__ void tok_phase(const PP P, int l) {
;     ...
;         if (smp || t >= 2018) {
;             float* op = smp ? out + O_CVS + ((size_t)(l * 32 + b) * 30 + 14 + t) * 256 : out + O_CVP + ((size_t)(l * 16 + b) * 30 + (t - 2018)) * 256;
; #pragma unroll
;             for (int i = 0; i < 4; ++i) { const int ch = lane + 64 * i; op[ch] = bf2f(hr[C_GA + ch]) * sigmoidf_(bf2f(hr[C_GG + ch])); }
.LBB0_477:
	s_or_b64 exec, exec, s[14:15]
	s_movk_i32 s8, 0x7e1
	v_cmp_lt_u32_e64 s[8:9], s8, v31
	s_or_b64 s[14:15], s[4:5], s[8:9]
	s_and_saveexec_b64 s[8:9], s[14:15]
	s_cbranch_execz .LBB0_468
	s_and_saveexec_b64 s[14:15], s[6:7]
	s_xor_b64 s[6:7], exec, s[14:15]
	v_add_u32_e32 v22, 0xfffff81e, v31
	v_add_u32_e32 v15, s16, v16
	v_ashrrev_i32_e32 v23, 31, v22
	v_mad_i64_i32 v[22:23], s[14:15], v15, 30, v[22:23]
	s_or_saveexec_b64 s[6:7], s[6:7]
	v_mov_b64_e32 v[28:29], 0xcc48000
	v_add_u32_e32 v15, s17, v16
	s_xor_b64 exec, exec, s[6:7]
	v_add_u32_e32 v16, 14, v31
	v_mov_b32_e32 v17, v25
	v_mad_i64_i32 v[22:23], s[14:15], v15, 30, v[16:17]
	v_mov_b64_e32 v[28:29], 0xd2e8000
	s_or_b64 exec, exec, s[6:7]
	v_lshl_add_u64 v[16:17], v[18:19], 0, v[24:25]
	s_movk_i32 s6, 0x1000
	v_add_co_u32_e64 v18, s[6:7], s6, v16
	global_load_ushort v24, v[16:17], off offset:3408
	global_load_ushort v32, v[16:17], off offset:3920
	global_load_ushort v33, v[16:17], off offset:3536
	global_load_ushort v34, v[16:17], off offset:4048
	global_load_ushort v35, v[16:17], off offset:3664
	v_addc_co_u32_e64 v19, s[6:7], 0, v17, s[6:7]
	global_load_ushort v36, v[18:19], off offset:80
	global_load_ushort v37, v[18:19], off offset:208
	global_load_ushort v38, v[16:17], off offset:3792
	v_lshl_add_u64 v[16:17], s[62:63], 0, v[28:29]
	v_lshlrev_b64 v[18:19], 10, v[22:23]
	v_mov_b32_e32 v21, v25
	v_lshl_add_u64 v[16:17], v[16:17], 0, v[18:19]
	v_lshl_add_u64 v[16:17], v[16:17], 0, v[20:21]
	v_cmp_eq_u32_e64 s[6:7], 0, v31
	s_and_b64 s[4:5], s[4:5], s[6:7]
	s_waitcnt vmcnt(7)
	v_lshlrev_b32_e32 v18, 16, v24
	s_waitcnt vmcnt(6)
	v_lshlrev_b32_e32 v19, 16, v32
	v_mul_f32_e32 v19, 0xbfb8aa3b, v19
	s_waitcnt vmcnt(4)
	v_lshlrev_b32_e32 v21, 16, v34
	v_mul_f32_e32 v21, 0xbfb8aa3b, v21
	s_waitcnt vmcnt(2)
	v_lshlrev_b32_e32 v23, 16, v36
	s_waitcnt vmcnt(1)
	v_lshlrev_b32_e32 v28, 16, v37
	v_exp_f32_e32 v19, v19
	v_mul_f32_e32 v23, 0xbfb8aa3b, v23
	v_exp_f32_e32 v21, v21
	v_mul_f32_e32 v28, 0xbfb8aa3b, v28
	v_exp_f32_e32 v23, v23
	v_exp_f32_e32 v28, v28
	v_add_f32_e32 v19, 1.0, v19
	v_add_f32_e32 v21, 1.0, v21
	v_rcp_f32_e32 v19, v19
	v_add_f32_e32 v23, 1.0, v23
	v_rcp_f32_e32 v21, v21
	v_add_f32_e32 v28, 1.0, v28
	v_rcp_f32_e32 v23, v23
	v_rcp_f32_e32 v28, v28
	v_lshlrev_b32_e32 v20, 16, v33
	v_lshlrev_b32_e32 v22, 16, v35
	v_mul_f32_e32 v18, v19, v18
	s_waitcnt vmcnt(0)
	v_lshlrev_b32_e32 v24, 16, v38
	v_mul_f32_e32 v19, v21, v20
	global_store_dword v[16:17], v18, off
	global_store_dword v[16:17], v19, off offset:256
	v_mul_f32_e32 v18, v23, v22
	v_mul_f32_e32 v19, v28, v24
	global_store_dword v[16:17], v18, off offset:512
	global_store_dword v[16:17], v19, off offset:768
	s_and_b64 exec, exec, s[4:5]
	s_cbranch_execz .LBB0_468
; __device__ __forceinline__ void tok_phase(const PP P, int l) {
;     ...
;             if (smp && t == 0) {
;                 const float* sc = KIN(6) + ((size_t)(l * 32 + b) * 30 + 16) * 256; float* o2 = out + O_CVS + (size_t)(l * 32 + b) * 30 * 256;
;                 for (int e = lane; e < 14 * 256; e += 64) o2[e] = sc[e];
;             }
	s_load_dwordx2 s[4:5], s[0:1], 48
	s_waitcnt lgkmcnt(0)
	s_movk_i32 s14, 0x7800
	v_lshl_add_u64 v[18:19], s[4:5], 0, v[26:27]
	v_mad_i64_i32 v[16:17], s[6:7], v15, s14, v[12:13]
	v_lshl_add_u64 v[18:19], v[18:19], 0, s[76:77]
	v_mad_i64_i32 v[18:19], s[4:5], v15, s14, v[18:19]
	s_mov_b64 s[6:7], 0
	v_mov_b32_e32 v15, v30
	s_mov_b64 s[4:5], 0x1000
	v_lshl_add_u64 v[126:127], v[18:19], 0, s[4:5]
	v_lshl_add_u64 v[128:129], v[126:127], 0, s[4:5]
	v_lshl_add_u64 v[130:131], v[128:129], 0, s[4:5]
	global_load_dword v70, v[18:19], off
	global_load_dword v71, v[18:19], off offset:256
	global_load_dword v72, v[18:19], off offset:512
	global_load_dword v73, v[18:19], off offset:768
	global_load_dword v74, v[18:19], off offset:1024
	global_load_dword v75, v[18:19], off offset:1280
	global_load_dword v76, v[18:19], off offset:1536
	global_load_dword v77, v[18:19], off offset:1792
	global_load_dword v78, v[18:19], off offset:2048
	global_load_dword v79, v[18:19], off offset:2304
	global_load_dword v80, v[18:19], off offset:2560
	global_load_dword v81, v[18:19], off offset:2816
	global_load_dword v82, v[18:19], off offset:3072
	global_load_dword v83, v[18:19], off offset:3328
	global_load_dword v84, v[18:19], off offset:3584
	global_load_dword v85, v[18:19], off offset:3840
	global_load_dword v86, v[126:127], off
	global_load_dword v87, v[126:127], off offset:256
	global_load_dword v88, v[126:127], off offset:512
	global_load_dword v89, v[126:127], off offset:768
	global_load_dword v90, v[126:127], off offset:1024
	global_load_dword v91, v[126:127], off offset:1280
	global_load_dword v92, v[126:127], off offset:1536
	global_load_dword v93, v[126:127], off offset:1792
	global_load_dword v94, v[126:127], off offset:2048
	global_load_dword v95, v[126:127], off offset:2304
	global_load_dword v96, v[126:127], off offset:2560
	global_load_dword v97, v[126:127], off offset:2816
	global_load_dword v98, v[126:127], off offset:3072
	global_load_dword v99, v[126:127], off offset:3328
	global_load_dword v100, v[126:127], off offset:3584
	global_load_dword v101, v[126:127], off offset:3840
	global_load_dword v102, v[128:129], off
	global_load_dword v103, v[128:129], off offset:256
	global_load_dword v104, v[128:129], off offset:512
	global_load_dword v105, v[128:129], off offset:768
	global_load_dword v106, v[128:129], off offset:1024
	global_load_dword v107, v[128:129], off offset:1280
	global_load_dword v108, v[128:129], off offset:1536
	global_load_dword v109, v[128:129], off offset:1792
	global_load_dword v110, v[128:129], off offset:2048
	global_load_dword v111, v[128:129], off offset:2304
	global_load_dword v112, v[128:129], off offset:2560
	global_load_dword v113, v[128:129], off offset:2816
	global_load_dword v114, v[128:129], off offset:3072
	global_load_dword v115, v[128:129], off offset:3328
	global_load_dword v116, v[128:129], off offset:3584
	global_load_dword v117, v[128:129], off offset:3840
	global_load_dword v118, v[130:131], off
	global_load_dword v119, v[130:131], off offset:256
	global_load_dword v120, v[130:131], off offset:512
	global_load_dword v121, v[130:131], off offset:768
	global_load_dword v122, v[130:131], off offset:1024
	global_load_dword v123, v[130:131], off offset:1280
	global_load_dword v124, v[130:131], off offset:1536
	global_load_dword v125, v[130:131], off offset:1792
	v_lshl_add_u64 v[132:133], v[16:17], 0, s[4:5]
	v_lshl_add_u64 v[134:135], v[132:133], 0, s[4:5]
	v_lshl_add_u64 v[136:137], v[134:135], 0, s[4:5]
	s_waitcnt vmcnt(40)
	global_store_dword v[16:17], v70, off
	global_store_dword v[16:17], v71, off offset:256
	global_store_dword v[16:17], v72, off offset:512
	global_store_dword v[16:17], v73, off offset:768
	global_store_dword v[16:17], v74, off offset:1024
	global_store_dword v[16:17], v75, off offset:1280
	global_store_dword v[16:17], v76, off offset:1536
	global_store_dword v[16:17], v77, off offset:1792
	global_store_dword v[16:17], v78, off offset:2048
	global_store_dword v[16:17], v79, off offset:2304
	global_store_dword v[16:17], v80, off offset:2560
	global_store_dword v[16:17], v81, off offset:2816
	global_store_dword v[16:17], v82, off offset:3072
	global_store_dword v[16:17], v83, off offset:3328
	global_store_dword v[16:17], v84, off offset:3584
	global_store_dword v[16:17], v85, off offset:3840
	s_waitcnt vmcnt(40)
	global_store_dword v[132:133], v86, off
	global_store_dword v[132:133], v87, off offset:256
	global_store_dword v[132:133], v88, off offset:512
	global_store_dword v[132:133], v89, off offset:768
	global_store_dword v[132:133], v90, off offset:1024
	global_store_dword v[132:133], v91, off offset:1280
	global_store_dword v[132:133], v92, off offset:1536
	global_store_dword v[132:133], v93, off offset:1792
	global_store_dword v[132:133], v94, off offset:2048
	global_store_dword v[132:133], v95, off offset:2304
	global_store_dword v[132:133], v96, off offset:2560
	global_store_dword v[132:133], v97, off offset:2816
	global_store_dword v[132:133], v98, off offset:3072
	global_store_dword v[132:133], v99, off offset:3328
	global_store_dword v[132:133], v100, off offset:3584
	global_store_dword v[132:133], v101, off offset:3840
	s_waitcnt vmcnt(40)
	global_store_dword v[134:135], v102, off
	global_store_dword v[134:135], v103, off offset:256
	global_store_dword v[134:135], v104, off offset:512
	global_store_dword v[134:135], v105, off offset:768
	global_store_dword v[134:135], v106, off offset:1024
	global_store_dword v[134:135], v107, off offset:1280
	global_store_dword v[134:135], v108, off offset:1536
	global_store_dword v[134:135], v109, off offset:1792
	global_store_dword v[134:135], v110, off offset:2048
	global_store_dword v[134:135], v111, off offset:2304
	global_store_dword v[134:135], v112, off offset:2560
	global_store_dword v[134:135], v113, off offset:2816
	global_store_dword v[134:135], v114, off offset:3072
	global_store_dword v[134:135], v115, off offset:3328
	global_store_dword v[134:135], v116, off offset:3584
	global_store_dword v[134:135], v117, off offset:3840
	s_waitcnt vmcnt(48)
	global_store_dword v[136:137], v118, off
	global_store_dword v[136:137], v119, off offset:256
	global_store_dword v[136:137], v120, off offset:512
	global_store_dword v[136:137], v121, off offset:768
	global_store_dword v[136:137], v122, off offset:1024
	global_store_dword v[136:137], v123, off offset:1280
	global_store_dword v[136:137], v124, off offset:1536
	global_store_dword v[136:137], v125, off offset:1792
	s_branch .LBB0_468

; __device__ __forceinline__ void prep_phase(const PP P, LAS unsigned char* lds, const int wl, const bool do_rest) {
;     ...
; #pragma unroll
;         for (int kk = ty; kk < 64; kk += 8) tile[kk * 65 + tx] = valid ? src[(size_t)(k0 + kk) * ld + col0 + tx] : 0.f;
.LBB0_725:
	s_mul_i32 s38, s38, s44
	s_sub_i32 s36, s41, s38
	s_lshl_b32 s36, s36, 6
	s_and_saveexec_b64 s[38:39], s[4:5]
	s_cbranch_execz .LBB0_730
	v_or_b32_e32 v4, s43, v0
	s_movk_i32 s37, 0x8a8
	v_cmp_gt_i32_e32 vcc, s37, v4
	s_ashr_i32 s41, s40, 31
	s_or_b64 s[26:27], s[26:27], vcc
	s_lshl_b64 s[40:41], s[40:41], 2
	s_add_u32 s28, s28, s40
	s_addc_u32 s29, s29, s41
	v_lshlrev_b32_e32 v24, 2, v0
	v_lshl_add_u64 v[4:5], s[28:29], 0, v[24:25]
	s_mov_b64 s[28:29], 0
	v_mov_b32_e32 v6, v10
	v_mov_b32_e32 v7, v2
	v_add_u32_e32 v40, s36, v2
	v_mul_lo_u32 v40, v40, s30
	v_mov_b32_e32 v41, v25
	v_lshl_add_u64 v[40:41], v[40:41], 2, v[4:5]
	s_lshl_b32 s44, s30, 5
	s_mov_b32 s45, 0
	v_lshl_add_u64 v[42:43], v[40:41], 0, s[44:45]
	v_lshl_add_u64 v[44:45], v[42:43], 0, s[44:45]
	v_lshl_add_u64 v[46:47], v[44:45], 0, s[44:45]
	v_lshl_add_u64 v[48:49], v[46:47], 0, s[44:45]
	v_lshl_add_u64 v[50:51], v[48:49], 0, s[44:45]
	v_lshl_add_u64 v[52:53], v[50:51], 0, s[44:45]
	v_lshl_add_u64 v[54:55], v[52:53], 0, s[44:45]
	v_mov_b32_e32 v30, 0
	v_mov_b32_e32 v31, 0
	v_mov_b32_e32 v32, 0
	v_mov_b32_e32 v33, 0
	v_mov_b32_e32 v34, 0
	v_mov_b32_e32 v35, 0
	v_mov_b32_e32 v36, 0
	v_mov_b32_e32 v37, 0
	s_and_saveexec_b64 s[40:41], s[26:27]
	s_cbranch_execz .Lprepb_nold
	global_load_dword v30, v[40:41], off
	global_load_dword v31, v[42:43], off
	global_load_dword v32, v[44:45], off
	global_load_dword v33, v[46:47], off
	global_load_dword v34, v[48:49], off
	global_load_dword v35, v[50:51], off
	global_load_dword v36, v[52:53], off
	global_load_dword v37, v[54:55], off
.Lprepb_nold:
	s_or_b64 exec, exec, s[40:41]
	s_waitcnt vmcnt(7)
	ds_write_b32 v10, v30
	s_waitcnt vmcnt(6)
	ds_write_b32 v10, v31 offset:2080
	s_waitcnt vmcnt(5)
	ds_write_b32 v10, v32 offset:4160
	s_waitcnt vmcnt(4)
	ds_write_b32 v10, v33 offset:6240
	s_waitcnt vmcnt(3)
	ds_write_b32 v10, v34 offset:8320
	s_waitcnt vmcnt(2)
	ds_write_b32 v10, v35 offset:10400
	s_waitcnt vmcnt(1)
	ds_write_b32 v10, v36 offset:12480
	s_waitcnt vmcnt(0)
	ds_write_b32 v10, v37 offset:14560
